# state pass with 4 register sets of prefetch instead of 8 (shallower in-flight window)
# baseline (speedup 1.0000x reference)
.LBB0_463:
	s_or_b64 exec, exec, s[2:3]
	v_readlane_b32 s0, v250, 18
	v_readlane_b32 s1, v250, 3
	v_readfirstlane_b32 s2, v0
	v_and_b32_e32 v1, 63, v0
	v_and_b32_e32 v12, 15, v1
	v_lshrrev_b32_e32 v13, 4, v1
	s_lshr_b32 s2, s2, 6
	s_and_b32 s3, s2, 1
	s_lshr_b32 s4, s2, 1
	s_and_b32 s1, s1, 1
	s_ashr_i32 s0, s0, 1
	s_lshl_b32 s0, s0, 19
	s_lshr_b32 s16, s0, 6
	s_mov_b32 s17, 0
	s_lshl_b32 s5, s4, 11
	v_lshl_add_u32 v14, v1, 4, s5
	v_mov_b32_e32 v15, 0
	s_lshl_b32 s5, s4, 4
	v_add_u32_e32 v16, s5, v12
	v_lshlrev_b32_e32 v16, 6, v16
	s_lshl_b32 s5, s1, 5
	v_lshl_add_u32 v17, v13, 2, s5
	v_add_u32_e32 v16, v16, v17
	v_lshlrev_b32_e32 v16, 1, v16
	v_mov_b32_e32 v17, 0
	s_lshl_b32 s5, s1, 3
	s_add_i32 s5, s5, s4
	s_lshl_b32 s5, s5, 9
	v_lshl_add_u32 v18, v1, 3, s5
	v_mov_b32_e32 v19, 0
	s_mov_b32 s8, 0x2000
	s_mov_b32 s9, 0
	v_mul_u32_u24_e32 v10, 0xa0, v12
	s_lshl_b32 s5, s4, 5
	v_lshl_add_u32 v11, v13, 3, s5
	v_add_u32_e32 v11, v11, v10
	v_lshl_add_u32 v10, v13, 4, v10
	s_cmp_eq_u32 s3, 0
	s_cbranch_scc0 .Lsp_hrole
	s_add_u32 s6, s58, s0
	s_addc_u32 s7, s59, 0
	v_lshl_add_u64 v[2:3], s[6:7], 0, v[14:15]
	s_add_u32 s6, s48, s0
	s_addc_u32 s7, s49, 0
	v_lshl_add_u64 v[6:7], s[6:7], 0, v[16:17]
	v_lshl_add_u64 v[182:183], s[6:7], 0, v[16:17]
	global_load_dwordx4 v[20:23], v[2:3], off
	global_load_dwordx4 v[24:27], v[2:3], off offset:1024
	global_load_dwordx2 v[28:29], v[6:7], off
	global_load_dwordx2 v[30:31], v[6:7], off offset:32
	v_lshl_add_u64 v[2:3], v[2:3], 0, s[8:9]
	v_lshl_add_u64 v[6:7], v[6:7], 0, s[8:9]
	global_load_dwordx4 v[32:35], v[2:3], off
	global_load_dwordx4 v[36:39], v[2:3], off offset:1024
	global_load_dwordx2 v[40:41], v[6:7], off
	global_load_dwordx2 v[42:43], v[6:7], off offset:32
	v_lshl_add_u64 v[2:3], v[2:3], 0, s[8:9]
	v_lshl_add_u64 v[6:7], v[6:7], 0, s[8:9]
	global_load_dwordx4 v[44:47], v[2:3], off
	global_load_dwordx4 v[48:51], v[2:3], off offset:1024
	global_load_dwordx2 v[52:53], v[6:7], off
	global_load_dwordx2 v[54:55], v[6:7], off offset:32
	v_lshl_add_u64 v[2:3], v[2:3], 0, s[8:9]
	v_lshl_add_u64 v[6:7], v[6:7], 0, s[8:9]
	s_waitcnt lgkmcnt(0)
	s_barrier
	global_load_dwordx4 v[56:59], v[2:3], off
	global_load_dwordx4 v[60:63], v[2:3], off offset:1024
	global_load_dwordx2 v[64:65], v[6:7], off
	global_load_dwordx2 v[66:67], v[6:7], off offset:32
	v_lshl_add_u64 v[2:3], v[2:3], 0, s[8:9]
	v_lshl_add_u64 v[6:7], v[6:7], 0, s[8:9]
	ds_read_b128 v[184:187], v10
	ds_read_b128 v[192:195], v10 offset:2560
	ds_read_b128 v[188:191], v10 offset:64
	ds_read_b128 v[196:199], v10 offset:2624
	s_waitcnt vmcnt(12)
	v_lshlrev_b32_e32 v200, 16, v28
	v_and_b32_e32 v201, 0xffff0000, v28
	v_lshlrev_b32_e32 v202, 16, v29
	v_and_b32_e32 v203, 0xffff0000, v29
	v_lshlrev_b32_e32 v204, 16, v30
	v_and_b32_e32 v205, 0xffff0000, v30
	v_lshlrev_b32_e32 v206, 16, v31
	v_and_b32_e32 v207, 0xffff0000, v31
	s_waitcnt lgkmcnt(2)
	v_mfma_f32_16x16x32_bf16 v[200:203], v[184:187], v[20:23], v[200:203]
	v_mfma_f32_16x16x32_bf16 v[204:207], v[192:195], v[20:23], v[204:207]
	s_waitcnt lgkmcnt(0)
	v_mfma_f32_16x16x32_bf16 v[200:203], v[188:191], v[24:27], v[200:203]
	v_mfma_f32_16x16x32_bf16 v[204:207], v[196:199], v[24:27], v[204:207]
	s_nop 6
	v_cvt_pk_bf16_f32 v200, v200, v201
	v_cvt_pk_bf16_f32 v201, v202, v203
	v_cvt_pk_bf16_f32 v204, v204, v205
	v_cvt_pk_bf16_f32 v205, v206, v207
	global_store_dwordx2 v[182:183], v[200:201], off
	global_store_dwordx2 v[182:183], v[204:205], off offset:32
	v_lshl_add_u64 v[182:183], v[182:183], 0, s[8:9]
	s_waitcnt lgkmcnt(0)
	s_barrier
	global_load_dwordx4 v[20:23], v[2:3], off
	global_load_dwordx4 v[24:27], v[2:3], off offset:1024
	global_load_dwordx2 v[28:29], v[6:7], off
	global_load_dwordx2 v[30:31], v[6:7], off offset:32
	v_lshl_add_u64 v[2:3], v[2:3], 0, s[8:9]
	v_lshl_add_u64 v[6:7], v[6:7], 0, s[8:9]
	ds_read_b128 v[184:187], v10 offset:5120
	ds_read_b128 v[192:195], v10 offset:7680
	ds_read_b128 v[188:191], v10 offset:5184
	ds_read_b128 v[196:199], v10 offset:7744
	s_waitcnt vmcnt(14)
	v_lshlrev_b32_e32 v200, 16, v40
	v_and_b32_e32 v201, 0xffff0000, v40
	v_lshlrev_b32_e32 v202, 16, v41
	v_and_b32_e32 v203, 0xffff0000, v41
	v_lshlrev_b32_e32 v204, 16, v42
	v_and_b32_e32 v205, 0xffff0000, v42
	v_lshlrev_b32_e32 v206, 16, v43
	v_and_b32_e32 v207, 0xffff0000, v43
	s_waitcnt lgkmcnt(2)
	v_mfma_f32_16x16x32_bf16 v[200:203], v[184:187], v[32:35], v[200:203]
	v_mfma_f32_16x16x32_bf16 v[204:207], v[192:195], v[32:35], v[204:207]
	s_waitcnt lgkmcnt(0)
	v_mfma_f32_16x16x32_bf16 v[200:203], v[188:191], v[36:39], v[200:203]
	v_mfma_f32_16x16x32_bf16 v[204:207], v[196:199], v[36:39], v[204:207]
	s_nop 6
	v_cvt_pk_bf16_f32 v200, v200, v201
	v_cvt_pk_bf16_f32 v201, v202, v203
	v_cvt_pk_bf16_f32 v204, v204, v205
	v_cvt_pk_bf16_f32 v205, v206, v207
	global_store_dwordx2 v[182:183], v[200:201], off
	global_store_dwordx2 v[182:183], v[204:205], off offset:32
	v_lshl_add_u64 v[182:183], v[182:183], 0, s[8:9]
	s_waitcnt lgkmcnt(0)
	s_barrier
	global_load_dwordx4 v[32:35], v[2:3], off
	global_load_dwordx4 v[36:39], v[2:3], off offset:1024
	global_load_dwordx2 v[40:41], v[6:7], off
	global_load_dwordx2 v[42:43], v[6:7], off offset:32
	v_lshl_add_u64 v[2:3], v[2:3], 0, s[8:9]
	v_lshl_add_u64 v[6:7], v[6:7], 0, s[8:9]
	ds_read_b128 v[184:187], v10
	ds_read_b128 v[192:195], v10 offset:2560
	ds_read_b128 v[188:191], v10 offset:64
	ds_read_b128 v[196:199], v10 offset:2624
	s_waitcnt vmcnt(16)
	v_lshlrev_b32_e32 v200, 16, v52
	v_and_b32_e32 v201, 0xffff0000, v52
	v_lshlrev_b32_e32 v202, 16, v53
	v_and_b32_e32 v203, 0xffff0000, v53
	v_lshlrev_b32_e32 v204, 16, v54
	v_and_b32_e32 v205, 0xffff0000, v54
	v_lshlrev_b32_e32 v206, 16, v55
	v_and_b32_e32 v207, 0xffff0000, v55
	s_waitcnt lgkmcnt(2)
	v_mfma_f32_16x16x32_bf16 v[200:203], v[184:187], v[44:47], v[200:203]
	v_mfma_f32_16x16x32_bf16 v[204:207], v[192:195], v[44:47], v[204:207]
	s_waitcnt lgkmcnt(0)
	v_mfma_f32_16x16x32_bf16 v[200:203], v[188:191], v[48:51], v[200:203]
	v_mfma_f32_16x16x32_bf16 v[204:207], v[196:199], v[48:51], v[204:207]
	s_nop 6
	v_cvt_pk_bf16_f32 v200, v200, v201
	v_cvt_pk_bf16_f32 v201, v202, v203
	v_cvt_pk_bf16_f32 v204, v204, v205
	v_cvt_pk_bf16_f32 v205, v206, v207
	global_store_dwordx2 v[182:183], v[200:201], off
	global_store_dwordx2 v[182:183], v[204:205], off offset:32
	v_lshl_add_u64 v[182:183], v[182:183], 0, s[8:9]
	s_waitcnt lgkmcnt(0)
	s_barrier
	global_load_dwordx4 v[44:47], v[2:3], off
	global_load_dwordx4 v[48:51], v[2:3], off offset:1024
	global_load_dwordx2 v[52:53], v[6:7], off
	global_load_dwordx2 v[54:55], v[6:7], off offset:32
	v_lshl_add_u64 v[2:3], v[2:3], 0, s[8:9]
	v_lshl_add_u64 v[6:7], v[6:7], 0, s[8:9]
	ds_read_b128 v[184:187], v10 offset:5120
	ds_read_b128 v[192:195], v10 offset:7680
	ds_read_b128 v[188:191], v10 offset:5184
	ds_read_b128 v[196:199], v10 offset:7744
	s_waitcnt vmcnt(18)
	v_lshlrev_b32_e32 v200, 16, v64
	v_and_b32_e32 v201, 0xffff0000, v64
	v_lshlrev_b32_e32 v202, 16, v65
	v_and_b32_e32 v203, 0xffff0000, v65
	v_lshlrev_b32_e32 v204, 16, v66
	v_and_b32_e32 v205, 0xffff0000, v66
	v_lshlrev_b32_e32 v206, 16, v67
	v_and_b32_e32 v207, 0xffff0000, v67
	s_waitcnt lgkmcnt(2)
	v_mfma_f32_16x16x32_bf16 v[200:203], v[184:187], v[56:59], v[200:203]
	v_mfma_f32_16x16x32_bf16 v[204:207], v[192:195], v[56:59], v[204:207]
	s_waitcnt lgkmcnt(0)
	v_mfma_f32_16x16x32_bf16 v[200:203], v[188:191], v[60:63], v[200:203]
	v_mfma_f32_16x16x32_bf16 v[204:207], v[196:199], v[60:63], v[204:207]
	s_nop 6
	v_cvt_pk_bf16_f32 v200, v200, v201
	v_cvt_pk_bf16_f32 v201, v202, v203
	v_cvt_pk_bf16_f32 v204, v204, v205
	v_cvt_pk_bf16_f32 v205, v206, v207
	global_store_dwordx2 v[182:183], v[200:201], off
	global_store_dwordx2 v[182:183], v[204:205], off offset:32
	v_lshl_add_u64 v[182:183], v[182:183], 0, s[8:9]
	s_waitcnt lgkmcnt(0)
	s_barrier
	s_mov_b32 s10, 14
.Lsp_loop0:
	global_load_dwordx4 v[56:59], v[2:3], off
	global_load_dwordx4 v[60:63], v[2:3], off offset:1024
	global_load_dwordx2 v[64:65], v[6:7], off
	global_load_dwordx2 v[66:67], v[6:7], off offset:32
	v_lshl_add_u64 v[2:3], v[2:3], 0, s[8:9]
	v_lshl_add_u64 v[6:7], v[6:7], 0, s[8:9]
	ds_read_b128 v[184:187], v10
	ds_read_b128 v[192:195], v10 offset:2560
	ds_read_b128 v[188:191], v10 offset:64
	ds_read_b128 v[196:199], v10 offset:2624
	s_waitcnt vmcnt(18)
	v_lshlrev_b32_e32 v200, 16, v28
	v_and_b32_e32 v201, 0xffff0000, v28
	v_lshlrev_b32_e32 v202, 16, v29
	v_and_b32_e32 v203, 0xffff0000, v29
	v_lshlrev_b32_e32 v204, 16, v30
	v_and_b32_e32 v205, 0xffff0000, v30
	v_lshlrev_b32_e32 v206, 16, v31
	v_and_b32_e32 v207, 0xffff0000, v31
	s_waitcnt lgkmcnt(2)
	v_mfma_f32_16x16x32_bf16 v[200:203], v[184:187], v[20:23], v[200:203]
	v_mfma_f32_16x16x32_bf16 v[204:207], v[192:195], v[20:23], v[204:207]
	s_waitcnt lgkmcnt(0)
	v_mfma_f32_16x16x32_bf16 v[200:203], v[188:191], v[24:27], v[200:203]
	v_mfma_f32_16x16x32_bf16 v[204:207], v[196:199], v[24:27], v[204:207]
	s_nop 6
	v_cvt_pk_bf16_f32 v200, v200, v201
	v_cvt_pk_bf16_f32 v201, v202, v203
	v_cvt_pk_bf16_f32 v204, v204, v205
	v_cvt_pk_bf16_f32 v205, v206, v207
	global_store_dwordx2 v[182:183], v[200:201], off
	global_store_dwordx2 v[182:183], v[204:205], off offset:32
	v_lshl_add_u64 v[182:183], v[182:183], 0, s[8:9]
	s_waitcnt lgkmcnt(0)
	s_barrier
	global_load_dwordx4 v[20:23], v[2:3], off
	global_load_dwordx4 v[24:27], v[2:3], off offset:1024
	global_load_dwordx2 v[28:29], v[6:7], off
	global_load_dwordx2 v[30:31], v[6:7], off offset:32
	v_lshl_add_u64 v[2:3], v[2:3], 0, s[8:9]
	v_lshl_add_u64 v[6:7], v[6:7], 0, s[8:9]
	ds_read_b128 v[184:187], v10 offset:5120
	ds_read_b128 v[192:195], v10 offset:7680
	ds_read_b128 v[188:191], v10 offset:5184
	ds_read_b128 v[196:199], v10 offset:7744
	s_waitcnt vmcnt(18)
	v_lshlrev_b32_e32 v200, 16, v40
	v_and_b32_e32 v201, 0xffff0000, v40
	v_lshlrev_b32_e32 v202, 16, v41
	v_and_b32_e32 v203, 0xffff0000, v41
	v_lshlrev_b32_e32 v204, 16, v42
	v_and_b32_e32 v205, 0xffff0000, v42
	v_lshlrev_b32_e32 v206, 16, v43
	v_and_b32_e32 v207, 0xffff0000, v43
	s_waitcnt lgkmcnt(2)
	v_mfma_f32_16x16x32_bf16 v[200:203], v[184:187], v[32:35], v[200:203]
	v_mfma_f32_16x16x32_bf16 v[204:207], v[192:195], v[32:35], v[204:207]
	s_waitcnt lgkmcnt(0)
	v_mfma_f32_16x16x32_bf16 v[200:203], v[188:191], v[36:39], v[200:203]
	v_mfma_f32_16x16x32_bf16 v[204:207], v[196:199], v[36:39], v[204:207]
	s_nop 6
	v_cvt_pk_bf16_f32 v200, v200, v201
	v_cvt_pk_bf16_f32 v201, v202, v203
	v_cvt_pk_bf16_f32 v204, v204, v205
	v_cvt_pk_bf16_f32 v205, v206, v207
	global_store_dwordx2 v[182:183], v[200:201], off
	global_store_dwordx2 v[182:183], v[204:205], off offset:32
	v_lshl_add_u64 v[182:183], v[182:183], 0, s[8:9]
	s_waitcnt lgkmcnt(0)
	s_barrier
	global_load_dwordx4 v[32:35], v[2:3], off
	global_load_dwordx4 v[36:39], v[2:3], off offset:1024
	global_load_dwordx2 v[40:41], v[6:7], off
	global_load_dwordx2 v[42:43], v[6:7], off offset:32
	v_lshl_add_u64 v[2:3], v[2:3], 0, s[8:9]
	v_lshl_add_u64 v[6:7], v[6:7], 0, s[8:9]
	ds_read_b128 v[184:187], v10
	ds_read_b128 v[192:195], v10 offset:2560
	ds_read_b128 v[188:191], v10 offset:64
	ds_read_b128 v[196:199], v10 offset:2624
	s_waitcnt vmcnt(18)
	v_lshlrev_b32_e32 v200, 16, v52
	v_and_b32_e32 v201, 0xffff0000, v52
	v_lshlrev_b32_e32 v202, 16, v53
	v_and_b32_e32 v203, 0xffff0000, v53
	v_lshlrev_b32_e32 v204, 16, v54
	v_and_b32_e32 v205, 0xffff0000, v54
	v_lshlrev_b32_e32 v206, 16, v55
	v_and_b32_e32 v207, 0xffff0000, v55
	s_waitcnt lgkmcnt(2)
	v_mfma_f32_16x16x32_bf16 v[200:203], v[184:187], v[44:47], v[200:203]
	v_mfma_f32_16x16x32_bf16 v[204:207], v[192:195], v[44:47], v[204:207]
	s_waitcnt lgkmcnt(0)
	v_mfma_f32_16x16x32_bf16 v[200:203], v[188:191], v[48:51], v[200:203]
	v_mfma_f32_16x16x32_bf16 v[204:207], v[196:199], v[48:51], v[204:207]
	s_nop 6
	v_cvt_pk_bf16_f32 v200, v200, v201
	v_cvt_pk_bf16_f32 v201, v202, v203
	v_cvt_pk_bf16_f32 v204, v204, v205
	v_cvt_pk_bf16_f32 v205, v206, v207
	global_store_dwordx2 v[182:183], v[200:201], off
	global_store_dwordx2 v[182:183], v[204:205], off offset:32
	v_lshl_add_u64 v[182:183], v[182:183], 0, s[8:9]
	s_waitcnt lgkmcnt(0)
	s_barrier
	global_load_dwordx4 v[44:47], v[2:3], off
	global_load_dwordx4 v[48:51], v[2:3], off offset:1024
	global_load_dwordx2 v[52:53], v[6:7], off
	global_load_dwordx2 v[54:55], v[6:7], off offset:32
	v_lshl_add_u64 v[2:3], v[2:3], 0, s[8:9]
	v_lshl_add_u64 v[6:7], v[6:7], 0, s[8:9]
	ds_read_b128 v[184:187], v10 offset:5120
	ds_read_b128 v[192:195], v10 offset:7680
	ds_read_b128 v[188:191], v10 offset:5184
	ds_read_b128 v[196:199], v10 offset:7744
	s_waitcnt vmcnt(18)
	v_lshlrev_b32_e32 v200, 16, v64
	v_and_b32_e32 v201, 0xffff0000, v64
	v_lshlrev_b32_e32 v202, 16, v65
	v_and_b32_e32 v203, 0xffff0000, v65
	v_lshlrev_b32_e32 v204, 16, v66
	v_and_b32_e32 v205, 0xffff0000, v66
	v_lshlrev_b32_e32 v206, 16, v67
	v_and_b32_e32 v207, 0xffff0000, v67
	s_waitcnt lgkmcnt(2)
	v_mfma_f32_16x16x32_bf16 v[200:203], v[184:187], v[56:59], v[200:203]
	v_mfma_f32_16x16x32_bf16 v[204:207], v[192:195], v[56:59], v[204:207]
	s_waitcnt lgkmcnt(0)
	v_mfma_f32_16x16x32_bf16 v[200:203], v[188:191], v[60:63], v[200:203]
	v_mfma_f32_16x16x32_bf16 v[204:207], v[196:199], v[60:63], v[204:207]
	s_nop 6
	v_cvt_pk_bf16_f32 v200, v200, v201
	v_cvt_pk_bf16_f32 v201, v202, v203
	v_cvt_pk_bf16_f32 v204, v204, v205
	v_cvt_pk_bf16_f32 v205, v206, v207
	global_store_dwordx2 v[182:183], v[200:201], off
	global_store_dwordx2 v[182:183], v[204:205], off offset:32
	v_lshl_add_u64 v[182:183], v[182:183], 0, s[8:9]
	s_waitcnt lgkmcnt(0)
	s_barrier
	s_add_i32 s10, s10, -1
	s_cmp_lg_u32 s10, 0
	s_cbranch_scc1 .Lsp_loop0
	global_load_dwordx4 v[56:59], v[2:3], off
	global_load_dwordx4 v[60:63], v[2:3], off offset:1024
	global_load_dwordx2 v[64:65], v[6:7], off
	global_load_dwordx2 v[66:67], v[6:7], off offset:32
	v_lshl_add_u64 v[2:3], v[2:3], 0, s[8:9]
	v_lshl_add_u64 v[6:7], v[6:7], 0, s[8:9]
	ds_read_b128 v[184:187], v10
	ds_read_b128 v[192:195], v10 offset:2560
	ds_read_b128 v[188:191], v10 offset:64
	ds_read_b128 v[196:199], v10 offset:2624
	s_waitcnt vmcnt(18)
	v_lshlrev_b32_e32 v200, 16, v28
	v_and_b32_e32 v201, 0xffff0000, v28
	v_lshlrev_b32_e32 v202, 16, v29
	v_and_b32_e32 v203, 0xffff0000, v29
	v_lshlrev_b32_e32 v204, 16, v30
	v_and_b32_e32 v205, 0xffff0000, v30
	v_lshlrev_b32_e32 v206, 16, v31
	v_and_b32_e32 v207, 0xffff0000, v31
	s_waitcnt lgkmcnt(2)
	v_mfma_f32_16x16x32_bf16 v[200:203], v[184:187], v[20:23], v[200:203]
	v_mfma_f32_16x16x32_bf16 v[204:207], v[192:195], v[20:23], v[204:207]
	s_waitcnt lgkmcnt(0)
	v_mfma_f32_16x16x32_bf16 v[200:203], v[188:191], v[24:27], v[200:203]
	v_mfma_f32_16x16x32_bf16 v[204:207], v[196:199], v[24:27], v[204:207]
	s_nop 6
	v_cvt_pk_bf16_f32 v200, v200, v201
	v_cvt_pk_bf16_f32 v201, v202, v203
	v_cvt_pk_bf16_f32 v204, v204, v205
	v_cvt_pk_bf16_f32 v205, v206, v207
	global_store_dwordx2 v[182:183], v[200:201], off
	global_store_dwordx2 v[182:183], v[204:205], off offset:32
	v_lshl_add_u64 v[182:183], v[182:183], 0, s[8:9]
	s_waitcnt lgkmcnt(0)
	s_barrier
	ds_read_b128 v[184:187], v10 offset:5120
	ds_read_b128 v[192:195], v10 offset:7680
	ds_read_b128 v[188:191], v10 offset:5184
	ds_read_b128 v[196:199], v10 offset:7744
	s_waitcnt vmcnt(14)
	v_lshlrev_b32_e32 v200, 16, v40
	v_and_b32_e32 v201, 0xffff0000, v40
	v_lshlrev_b32_e32 v202, 16, v41
	v_and_b32_e32 v203, 0xffff0000, v41
	v_lshlrev_b32_e32 v204, 16, v42
	v_and_b32_e32 v205, 0xffff0000, v42
	v_lshlrev_b32_e32 v206, 16, v43
	v_and_b32_e32 v207, 0xffff0000, v43
	s_waitcnt lgkmcnt(2)
	v_mfma_f32_16x16x32_bf16 v[200:203], v[184:187], v[32:35], v[200:203]
	v_mfma_f32_16x16x32_bf16 v[204:207], v[192:195], v[32:35], v[204:207]
	s_waitcnt lgkmcnt(0)
	v_mfma_f32_16x16x32_bf16 v[200:203], v[188:191], v[36:39], v[200:203]
	v_mfma_f32_16x16x32_bf16 v[204:207], v[196:199], v[36:39], v[204:207]
	s_nop 6
	v_cvt_pk_bf16_f32 v200, v200, v201
	v_cvt_pk_bf16_f32 v201, v202, v203
	v_cvt_pk_bf16_f32 v204, v204, v205
	v_cvt_pk_bf16_f32 v205, v206, v207
	global_store_dwordx2 v[182:183], v[200:201], off
	global_store_dwordx2 v[182:183], v[204:205], off offset:32
	v_lshl_add_u64 v[182:183], v[182:183], 0, s[8:9]
	s_waitcnt lgkmcnt(0)
	s_barrier
	ds_read_b128 v[184:187], v10
	ds_read_b128 v[192:195], v10 offset:2560
	ds_read_b128 v[188:191], v10 offset:64
	ds_read_b128 v[196:199], v10 offset:2624
	s_waitcnt vmcnt(10)
	v_lshlrev_b32_e32 v200, 16, v52
	v_and_b32_e32 v201, 0xffff0000, v52
	v_lshlrev_b32_e32 v202, 16, v53
	v_and_b32_e32 v203, 0xffff0000, v53
	v_lshlrev_b32_e32 v204, 16, v54
	v_and_b32_e32 v205, 0xffff0000, v54
	v_lshlrev_b32_e32 v206, 16, v55
	v_and_b32_e32 v207, 0xffff0000, v55
	s_waitcnt lgkmcnt(2)
	v_mfma_f32_16x16x32_bf16 v[200:203], v[184:187], v[44:47], v[200:203]
	v_mfma_f32_16x16x32_bf16 v[204:207], v[192:195], v[44:47], v[204:207]
	s_waitcnt lgkmcnt(0)
	v_mfma_f32_16x16x32_bf16 v[200:203], v[188:191], v[48:51], v[200:203]
	v_mfma_f32_16x16x32_bf16 v[204:207], v[196:199], v[48:51], v[204:207]
	s_nop 6
	v_cvt_pk_bf16_f32 v200, v200, v201
	v_cvt_pk_bf16_f32 v201, v202, v203
	v_cvt_pk_bf16_f32 v204, v204, v205
	v_cvt_pk_bf16_f32 v205, v206, v207
	global_store_dwordx2 v[182:183], v[200:201], off
	global_store_dwordx2 v[182:183], v[204:205], off offset:32
	v_lshl_add_u64 v[182:183], v[182:183], 0, s[8:9]
	s_waitcnt lgkmcnt(0)
	s_barrier
	ds_read_b128 v[184:187], v10 offset:5120
	ds_read_b128 v[192:195], v10 offset:7680
	ds_read_b128 v[188:191], v10 offset:5184
	ds_read_b128 v[196:199], v10 offset:7744
	s_waitcnt vmcnt(6)
	v_lshlrev_b32_e32 v200, 16, v64
	v_and_b32_e32 v201, 0xffff0000, v64
	v_lshlrev_b32_e32 v202, 16, v65
	v_and_b32_e32 v203, 0xffff0000, v65
	v_lshlrev_b32_e32 v204, 16, v66
	v_and_b32_e32 v205, 0xffff0000, v66
	v_lshlrev_b32_e32 v206, 16, v67
	v_and_b32_e32 v207, 0xffff0000, v67
	s_waitcnt lgkmcnt(2)
	v_mfma_f32_16x16x32_bf16 v[200:203], v[184:187], v[56:59], v[200:203]
	v_mfma_f32_16x16x32_bf16 v[204:207], v[192:195], v[56:59], v[204:207]
	s_waitcnt lgkmcnt(0)
	v_mfma_f32_16x16x32_bf16 v[200:203], v[188:191], v[60:63], v[200:203]
	v_mfma_f32_16x16x32_bf16 v[204:207], v[196:199], v[60:63], v[204:207]
	s_nop 6
	v_cvt_pk_bf16_f32 v200, v200, v201
	v_cvt_pk_bf16_f32 v201, v202, v203
	v_cvt_pk_bf16_f32 v204, v204, v205
	v_cvt_pk_bf16_f32 v205, v206, v207
	global_store_dwordx2 v[182:183], v[200:201], off
	global_store_dwordx2 v[182:183], v[204:205], off offset:32
	v_lshl_add_u64 v[182:183], v[182:183], 0, s[8:9]
	s_waitcnt lgkmcnt(0)
	s_barrier
	s_branch .Lsp_done
.Lsp_hrole:
	s_add_u32 s6, s96, s0
	s_addc_u32 s7, s97, 0
	v_lshl_add_u64 v[2:3], s[6:7], 0, v[14:15]
	s_add_u32 s6, s88, s0
	s_addc_u32 s7, s89, 0
	v_lshl_add_u64 v[6:7], s[6:7], 0, v[18:19]
	global_load_dwordx4 v[20:23], v[2:3], off
	global_load_dwordx4 v[24:27], v[2:3], off offset:1024
	global_load_dwordx2 v[28:29], v[6:7], off
	global_load_dwordx2 v[30:31], v[6:7], off offset:2048
	v_lshl_add_u64 v[2:3], v[2:3], 0, s[8:9]
	v_lshl_add_u64 v[6:7], v[6:7], 0, s[8:9]
	global_load_dwordx4 v[32:35], v[2:3], off
	global_load_dwordx4 v[36:39], v[2:3], off offset:1024
	global_load_dwordx2 v[40:41], v[6:7], off
	global_load_dwordx2 v[42:43], v[6:7], off offset:2048
	v_lshl_add_u64 v[2:3], v[2:3], 0, s[8:9]
	v_lshl_add_u64 v[6:7], v[6:7], 0, s[8:9]
	global_load_dwordx4 v[44:47], v[2:3], off
	global_load_dwordx4 v[48:51], v[2:3], off offset:1024
	global_load_dwordx2 v[52:53], v[6:7], off
	global_load_dwordx2 v[54:55], v[6:7], off offset:2048
	v_lshl_add_u64 v[2:3], v[2:3], 0, s[8:9]
	v_lshl_add_u64 v[6:7], v[6:7], 0, s[8:9]
	s_waitcnt lgkmcnt(0)
	s_barrier
	global_load_dwordx4 v[56:59], v[2:3], off
	global_load_dwordx4 v[60:63], v[2:3], off offset:1024
	global_load_dwordx2 v[64:65], v[6:7], off
	global_load_dwordx2 v[66:67], v[6:7], off offset:2048
	v_lshl_add_u64 v[2:3], v[2:3], 0, s[8:9]
	v_lshl_add_u64 v[6:7], v[6:7], 0, s[8:9]
	ds_read_b128 v[184:187], v10
	ds_read_b128 v[192:195], v10 offset:2560
	ds_read_b128 v[188:191], v10 offset:64
	ds_read_b128 v[196:199], v10 offset:2624
	s_waitcnt vmcnt(12)
	v_lshlrev_b32_e32 v200, 16, v28
	v_and_b32_e32 v201, 0xffff0000, v28
	v_lshlrev_b32_e32 v202, 16, v29
	v_and_b32_e32 v203, 0xffff0000, v29
	v_lshlrev_b32_e32 v204, 16, v30
	v_and_b32_e32 v205, 0xffff0000, v30
	v_lshlrev_b32_e32 v206, 16, v31
	v_and_b32_e32 v207, 0xffff0000, v31
	s_waitcnt lgkmcnt(2)
	v_mfma_f32_16x16x32_bf16 v[200:203], v[20:23], v[184:187], v[200:203]
	v_mfma_f32_16x16x32_bf16 v[204:207], v[20:23], v[192:195], v[204:207]
	s_waitcnt lgkmcnt(0)
	v_mfma_f32_16x16x32_bf16 v[200:203], v[24:27], v[188:191], v[200:203]
	v_mfma_f32_16x16x32_bf16 v[204:207], v[24:27], v[196:199], v[204:207]
	s_nop 6
	v_cvt_pk_bf16_f32 v200, v200, v201
	v_cvt_pk_bf16_f32 v201, v202, v203
	v_cvt_pk_bf16_f32 v204, v204, v205
	v_cvt_pk_bf16_f32 v205, v206, v207
	ds_write_b64 v11, v[200:201] offset:5120
	ds_write_b64 v11, v[204:205] offset:7680
	s_waitcnt lgkmcnt(0)
	s_barrier
	global_load_dwordx4 v[20:23], v[2:3], off
	global_load_dwordx4 v[24:27], v[2:3], off offset:1024
	global_load_dwordx2 v[28:29], v[6:7], off
	global_load_dwordx2 v[30:31], v[6:7], off offset:2048
	v_lshl_add_u64 v[2:3], v[2:3], 0, s[8:9]
	v_lshl_add_u64 v[6:7], v[6:7], 0, s[8:9]
	ds_read_b128 v[184:187], v10 offset:5120
	ds_read_b128 v[192:195], v10 offset:7680
	ds_read_b128 v[188:191], v10 offset:5184
	ds_read_b128 v[196:199], v10 offset:7744
	s_waitcnt vmcnt(12)
	v_lshlrev_b32_e32 v200, 16, v40
	v_and_b32_e32 v201, 0xffff0000, v40
	v_lshlrev_b32_e32 v202, 16, v41
	v_and_b32_e32 v203, 0xffff0000, v41
	v_lshlrev_b32_e32 v204, 16, v42
	v_and_b32_e32 v205, 0xffff0000, v42
	v_lshlrev_b32_e32 v206, 16, v43
	v_and_b32_e32 v207, 0xffff0000, v43
	s_waitcnt lgkmcnt(2)
	v_mfma_f32_16x16x32_bf16 v[200:203], v[32:35], v[184:187], v[200:203]
	v_mfma_f32_16x16x32_bf16 v[204:207], v[32:35], v[192:195], v[204:207]
	s_waitcnt lgkmcnt(0)
	v_mfma_f32_16x16x32_bf16 v[200:203], v[36:39], v[188:191], v[200:203]
	v_mfma_f32_16x16x32_bf16 v[204:207], v[36:39], v[196:199], v[204:207]
	s_nop 6
	v_cvt_pk_bf16_f32 v200, v200, v201
	v_cvt_pk_bf16_f32 v201, v202, v203
	v_cvt_pk_bf16_f32 v204, v204, v205
	v_cvt_pk_bf16_f32 v205, v206, v207
	ds_write_b64 v11, v[200:201]
	ds_write_b64 v11, v[204:205] offset:2560
	s_waitcnt lgkmcnt(0)
	s_barrier
	global_load_dwordx4 v[32:35], v[2:3], off
	global_load_dwordx4 v[36:39], v[2:3], off offset:1024
	global_load_dwordx2 v[40:41], v[6:7], off
	global_load_dwordx2 v[42:43], v[6:7], off offset:2048
	v_lshl_add_u64 v[2:3], v[2:3], 0, s[8:9]
	v_lshl_add_u64 v[6:7], v[6:7], 0, s[8:9]
	ds_read_b128 v[184:187], v10
	ds_read_b128 v[192:195], v10 offset:2560
	ds_read_b128 v[188:191], v10 offset:64
	ds_read_b128 v[196:199], v10 offset:2624
	s_waitcnt vmcnt(12)
	v_lshlrev_b32_e32 v200, 16, v52
	v_and_b32_e32 v201, 0xffff0000, v52
	v_lshlrev_b32_e32 v202, 16, v53
	v_and_b32_e32 v203, 0xffff0000, v53
	v_lshlrev_b32_e32 v204, 16, v54
	v_and_b32_e32 v205, 0xffff0000, v54
	v_lshlrev_b32_e32 v206, 16, v55
	v_and_b32_e32 v207, 0xffff0000, v55
	s_waitcnt lgkmcnt(2)
	v_mfma_f32_16x16x32_bf16 v[200:203], v[44:47], v[184:187], v[200:203]
	v_mfma_f32_16x16x32_bf16 v[204:207], v[44:47], v[192:195], v[204:207]
	s_waitcnt lgkmcnt(0)
	v_mfma_f32_16x16x32_bf16 v[200:203], v[48:51], v[188:191], v[200:203]
	v_mfma_f32_16x16x32_bf16 v[204:207], v[48:51], v[196:199], v[204:207]
	s_nop 6
	v_cvt_pk_bf16_f32 v200, v200, v201
	v_cvt_pk_bf16_f32 v201, v202, v203
	v_cvt_pk_bf16_f32 v204, v204, v205
	v_cvt_pk_bf16_f32 v205, v206, v207
	ds_write_b64 v11, v[200:201] offset:5120
	ds_write_b64 v11, v[204:205] offset:7680
	s_waitcnt lgkmcnt(0)
	s_barrier
	global_load_dwordx4 v[44:47], v[2:3], off
	global_load_dwordx4 v[48:51], v[2:3], off offset:1024
	global_load_dwordx2 v[52:53], v[6:7], off
	global_load_dwordx2 v[54:55], v[6:7], off offset:2048
	v_lshl_add_u64 v[2:3], v[2:3], 0, s[8:9]
	v_lshl_add_u64 v[6:7], v[6:7], 0, s[8:9]
	ds_read_b128 v[184:187], v10 offset:5120
	ds_read_b128 v[192:195], v10 offset:7680
	ds_read_b128 v[188:191], v10 offset:5184
	ds_read_b128 v[196:199], v10 offset:7744
	s_waitcnt vmcnt(12)
	v_lshlrev_b32_e32 v200, 16, v64
	v_and_b32_e32 v201, 0xffff0000, v64
	v_lshlrev_b32_e32 v202, 16, v65
	v_and_b32_e32 v203, 0xffff0000, v65
	v_lshlrev_b32_e32 v204, 16, v66
	v_and_b32_e32 v205, 0xffff0000, v66
	v_lshlrev_b32_e32 v206, 16, v67
	v_and_b32_e32 v207, 0xffff0000, v67
	s_waitcnt lgkmcnt(2)
	v_mfma_f32_16x16x32_bf16 v[200:203], v[56:59], v[184:187], v[200:203]
	v_mfma_f32_16x16x32_bf16 v[204:207], v[56:59], v[192:195], v[204:207]
	s_waitcnt lgkmcnt(0)
	v_mfma_f32_16x16x32_bf16 v[200:203], v[60:63], v[188:191], v[200:203]
	v_mfma_f32_16x16x32_bf16 v[204:207], v[60:63], v[196:199], v[204:207]
	s_nop 6
	v_cvt_pk_bf16_f32 v200, v200, v201
	v_cvt_pk_bf16_f32 v201, v202, v203
	v_cvt_pk_bf16_f32 v204, v204, v205
	v_cvt_pk_bf16_f32 v205, v206, v207
	ds_write_b64 v11, v[200:201]
	ds_write_b64 v11, v[204:205] offset:2560
	s_waitcnt lgkmcnt(0)
	s_barrier
	s_mov_b32 s10, 14
.Lsp_loop1:
	global_load_dwordx4 v[56:59], v[2:3], off
	global_load_dwordx4 v[60:63], v[2:3], off offset:1024
	global_load_dwordx2 v[64:65], v[6:7], off
	global_load_dwordx2 v[66:67], v[6:7], off offset:2048
	v_lshl_add_u64 v[2:3], v[2:3], 0, s[8:9]
	v_lshl_add_u64 v[6:7], v[6:7], 0, s[8:9]
	ds_read_b128 v[184:187], v10
	ds_read_b128 v[192:195], v10 offset:2560
	ds_read_b128 v[188:191], v10 offset:64
	ds_read_b128 v[196:199], v10 offset:2624
	s_waitcnt vmcnt(12)
	v_lshlrev_b32_e32 v200, 16, v28
	v_and_b32_e32 v201, 0xffff0000, v28
	v_lshlrev_b32_e32 v202, 16, v29
	v_and_b32_e32 v203, 0xffff0000, v29
	v_lshlrev_b32_e32 v204, 16, v30
	v_and_b32_e32 v205, 0xffff0000, v30
	v_lshlrev_b32_e32 v206, 16, v31
	v_and_b32_e32 v207, 0xffff0000, v31
	s_waitcnt lgkmcnt(2)
	v_mfma_f32_16x16x32_bf16 v[200:203], v[20:23], v[184:187], v[200:203]
	v_mfma_f32_16x16x32_bf16 v[204:207], v[20:23], v[192:195], v[204:207]
	s_waitcnt lgkmcnt(0)
	v_mfma_f32_16x16x32_bf16 v[200:203], v[24:27], v[188:191], v[200:203]
	v_mfma_f32_16x16x32_bf16 v[204:207], v[24:27], v[196:199], v[204:207]
	s_nop 6
	v_cvt_pk_bf16_f32 v200, v200, v201
	v_cvt_pk_bf16_f32 v201, v202, v203
	v_cvt_pk_bf16_f32 v204, v204, v205
	v_cvt_pk_bf16_f32 v205, v206, v207
	ds_write_b64 v11, v[200:201] offset:5120
	ds_write_b64 v11, v[204:205] offset:7680
	s_waitcnt lgkmcnt(0)
	s_barrier
	global_load_dwordx4 v[20:23], v[2:3], off
	global_load_dwordx4 v[24:27], v[2:3], off offset:1024
	global_load_dwordx2 v[28:29], v[6:7], off
	global_load_dwordx2 v[30:31], v[6:7], off offset:2048
	v_lshl_add_u64 v[2:3], v[2:3], 0, s[8:9]
	v_lshl_add_u64 v[6:7], v[6:7], 0, s[8:9]
	ds_read_b128 v[184:187], v10 offset:5120
	ds_read_b128 v[192:195], v10 offset:7680
	ds_read_b128 v[188:191], v10 offset:5184
	ds_read_b128 v[196:199], v10 offset:7744
	s_waitcnt vmcnt(12)
	v_lshlrev_b32_e32 v200, 16, v40
	v_and_b32_e32 v201, 0xffff0000, v40
	v_lshlrev_b32_e32 v202, 16, v41
	v_and_b32_e32 v203, 0xffff0000, v41
	v_lshlrev_b32_e32 v204, 16, v42
	v_and_b32_e32 v205, 0xffff0000, v42
	v_lshlrev_b32_e32 v206, 16, v43
	v_and_b32_e32 v207, 0xffff0000, v43
	s_waitcnt lgkmcnt(2)
	v_mfma_f32_16x16x32_bf16 v[200:203], v[32:35], v[184:187], v[200:203]
	v_mfma_f32_16x16x32_bf16 v[204:207], v[32:35], v[192:195], v[204:207]
	s_waitcnt lgkmcnt(0)
	v_mfma_f32_16x16x32_bf16 v[200:203], v[36:39], v[188:191], v[200:203]
	v_mfma_f32_16x16x32_bf16 v[204:207], v[36:39], v[196:199], v[204:207]
	s_nop 6
	v_cvt_pk_bf16_f32 v200, v200, v201
	v_cvt_pk_bf16_f32 v201, v202, v203
	v_cvt_pk_bf16_f32 v204, v204, v205
	v_cvt_pk_bf16_f32 v205, v206, v207
	ds_write_b64 v11, v[200:201]
	ds_write_b64 v11, v[204:205] offset:2560
	s_waitcnt lgkmcnt(0)
	s_barrier
	global_load_dwordx4 v[32:35], v[2:3], off
	global_load_dwordx4 v[36:39], v[2:3], off offset:1024
	global_load_dwordx2 v[40:41], v[6:7], off
	global_load_dwordx2 v[42:43], v[6:7], off offset:2048
	v_lshl_add_u64 v[2:3], v[2:3], 0, s[8:9]
	v_lshl_add_u64 v[6:7], v[6:7], 0, s[8:9]
	ds_read_b128 v[184:187], v10
	ds_read_b128 v[192:195], v10 offset:2560
	ds_read_b128 v[188:191], v10 offset:64
	ds_read_b128 v[196:199], v10 offset:2624
	s_waitcnt vmcnt(12)
	v_lshlrev_b32_e32 v200, 16, v52
	v_and_b32_e32 v201, 0xffff0000, v52
	v_lshlrev_b32_e32 v202, 16, v53
	v_and_b32_e32 v203, 0xffff0000, v53
	v_lshlrev_b32_e32 v204, 16, v54
	v_and_b32_e32 v205, 0xffff0000, v54
	v_lshlrev_b32_e32 v206, 16, v55
	v_and_b32_e32 v207, 0xffff0000, v55
	s_waitcnt lgkmcnt(2)
	v_mfma_f32_16x16x32_bf16 v[200:203], v[44:47], v[184:187], v[200:203]
	v_mfma_f32_16x16x32_bf16 v[204:207], v[44:47], v[192:195], v[204:207]
	s_waitcnt lgkmcnt(0)
	v_mfma_f32_16x16x32_bf16 v[200:203], v[48:51], v[188:191], v[200:203]
	v_mfma_f32_16x16x32_bf16 v[204:207], v[48:51], v[196:199], v[204:207]
	s_nop 6
	v_cvt_pk_bf16_f32 v200, v200, v201
	v_cvt_pk_bf16_f32 v201, v202, v203
	v_cvt_pk_bf16_f32 v204, v204, v205
	v_cvt_pk_bf16_f32 v205, v206, v207
	ds_write_b64 v11, v[200:201] offset:5120
	ds_write_b64 v11, v[204:205] offset:7680
	s_waitcnt lgkmcnt(0)
	s_barrier
	global_load_dwordx4 v[44:47], v[2:3], off
	global_load_dwordx4 v[48:51], v[2:3], off offset:1024
	global_load_dwordx2 v[52:53], v[6:7], off
	global_load_dwordx2 v[54:55], v[6:7], off offset:2048
	v_lshl_add_u64 v[2:3], v[2:3], 0, s[8:9]
	v_lshl_add_u64 v[6:7], v[6:7], 0, s[8:9]
	ds_read_b128 v[184:187], v10 offset:5120
	ds_read_b128 v[192:195], v10 offset:7680
	ds_read_b128 v[188:191], v10 offset:5184
	ds_read_b128 v[196:199], v10 offset:7744
	s_waitcnt vmcnt(12)
	v_lshlrev_b32_e32 v200, 16, v64
	v_and_b32_e32 v201, 0xffff0000, v64
	v_lshlrev_b32_e32 v202, 16, v65
	v_and_b32_e32 v203, 0xffff0000, v65
	v_lshlrev_b32_e32 v204, 16, v66
	v_and_b32_e32 v205, 0xffff0000, v66
	v_lshlrev_b32_e32 v206, 16, v67
	v_and_b32_e32 v207, 0xffff0000, v67
	s_waitcnt lgkmcnt(2)
	v_mfma_f32_16x16x32_bf16 v[200:203], v[56:59], v[184:187], v[200:203]
	v_mfma_f32_16x16x32_bf16 v[204:207], v[56:59], v[192:195], v[204:207]
	s_waitcnt lgkmcnt(0)
	v_mfma_f32_16x16x32_bf16 v[200:203], v[60:63], v[188:191], v[200:203]
	v_mfma_f32_16x16x32_bf16 v[204:207], v[60:63], v[196:199], v[204:207]
	s_nop 6
	v_cvt_pk_bf16_f32 v200, v200, v201
	v_cvt_pk_bf16_f32 v201, v202, v203
	v_cvt_pk_bf16_f32 v204, v204, v205
	v_cvt_pk_bf16_f32 v205, v206, v207
	ds_write_b64 v11, v[200:201]
	ds_write_b64 v11, v[204:205] offset:2560
	s_waitcnt lgkmcnt(0)
	s_barrier
	s_add_i32 s10, s10, -1
	s_cmp_lg_u32 s10, 0
	s_cbranch_scc1 .Lsp_loop1
	global_load_dwordx4 v[56:59], v[2:3], off
	global_load_dwordx4 v[60:63], v[2:3], off offset:1024
	global_load_dwordx2 v[64:65], v[6:7], off
	global_load_dwordx2 v[66:67], v[6:7], off offset:2048
	v_lshl_add_u64 v[2:3], v[2:3], 0, s[8:9]
	v_lshl_add_u64 v[6:7], v[6:7], 0, s[8:9]
	ds_read_b128 v[184:187], v10
	ds_read_b128 v[192:195], v10 offset:2560
	ds_read_b128 v[188:191], v10 offset:64
	ds_read_b128 v[196:199], v10 offset:2624
	s_waitcnt vmcnt(12)
	v_lshlrev_b32_e32 v200, 16, v28
	v_and_b32_e32 v201, 0xffff0000, v28
	v_lshlrev_b32_e32 v202, 16, v29
	v_and_b32_e32 v203, 0xffff0000, v29
	v_lshlrev_b32_e32 v204, 16, v30
	v_and_b32_e32 v205, 0xffff0000, v30
	v_lshlrev_b32_e32 v206, 16, v31
	v_and_b32_e32 v207, 0xffff0000, v31
	s_waitcnt lgkmcnt(2)
	v_mfma_f32_16x16x32_bf16 v[200:203], v[20:23], v[184:187], v[200:203]
	v_mfma_f32_16x16x32_bf16 v[204:207], v[20:23], v[192:195], v[204:207]
	s_waitcnt lgkmcnt(0)
	v_mfma_f32_16x16x32_bf16 v[200:203], v[24:27], v[188:191], v[200:203]
	v_mfma_f32_16x16x32_bf16 v[204:207], v[24:27], v[196:199], v[204:207]
	s_nop 6
	v_cvt_pk_bf16_f32 v200, v200, v201
	v_cvt_pk_bf16_f32 v201, v202, v203
	v_cvt_pk_bf16_f32 v204, v204, v205
	v_cvt_pk_bf16_f32 v205, v206, v207
	ds_write_b64 v11, v[200:201] offset:5120
	ds_write_b64 v11, v[204:205] offset:7680
	s_waitcnt lgkmcnt(0)
	s_barrier
	ds_read_b128 v[184:187], v10 offset:5120
	ds_read_b128 v[192:195], v10 offset:7680
	ds_read_b128 v[188:191], v10 offset:5184
	ds_read_b128 v[196:199], v10 offset:7744
	s_waitcnt vmcnt(8)
	v_lshlrev_b32_e32 v200, 16, v40
	v_and_b32_e32 v201, 0xffff0000, v40
	v_lshlrev_b32_e32 v202, 16, v41
	v_and_b32_e32 v203, 0xffff0000, v41
	v_lshlrev_b32_e32 v204, 16, v42
	v_and_b32_e32 v205, 0xffff0000, v42
	v_lshlrev_b32_e32 v206, 16, v43
	v_and_b32_e32 v207, 0xffff0000, v43
	s_waitcnt lgkmcnt(2)
	v_mfma_f32_16x16x32_bf16 v[200:203], v[32:35], v[184:187], v[200:203]
	v_mfma_f32_16x16x32_bf16 v[204:207], v[32:35], v[192:195], v[204:207]
	s_waitcnt lgkmcnt(0)
	v_mfma_f32_16x16x32_bf16 v[200:203], v[36:39], v[188:191], v[200:203]
	v_mfma_f32_16x16x32_bf16 v[204:207], v[36:39], v[196:199], v[204:207]
	s_nop 6
	v_cvt_pk_bf16_f32 v200, v200, v201
	v_cvt_pk_bf16_f32 v201, v202, v203
	v_cvt_pk_bf16_f32 v204, v204, v205
	v_cvt_pk_bf16_f32 v205, v206, v207
	ds_write_b64 v11, v[200:201]
	ds_write_b64 v11, v[204:205] offset:2560
	s_waitcnt lgkmcnt(0)
	s_barrier
	ds_read_b128 v[184:187], v10
	ds_read_b128 v[192:195], v10 offset:2560
	ds_read_b128 v[188:191], v10 offset:64
	ds_read_b128 v[196:199], v10 offset:2624
	s_waitcnt vmcnt(4)
	v_lshlrev_b32_e32 v200, 16, v52
	v_and_b32_e32 v201, 0xffff0000, v52
	v_lshlrev_b32_e32 v202, 16, v53
	v_and_b32_e32 v203, 0xffff0000, v53
	v_lshlrev_b32_e32 v204, 16, v54
	v_and_b32_e32 v205, 0xffff0000, v54
	v_lshlrev_b32_e32 v206, 16, v55
	v_and_b32_e32 v207, 0xffff0000, v55
	s_waitcnt lgkmcnt(2)
	v_mfma_f32_16x16x32_bf16 v[200:203], v[44:47], v[184:187], v[200:203]
	v_mfma_f32_16x16x32_bf16 v[204:207], v[44:47], v[192:195], v[204:207]
	s_waitcnt lgkmcnt(0)
	v_mfma_f32_16x16x32_bf16 v[200:203], v[48:51], v[188:191], v[200:203]
	v_mfma_f32_16x16x32_bf16 v[204:207], v[48:51], v[196:199], v[204:207]
	s_nop 6
	v_cvt_pk_bf16_f32 v200, v200, v201
	v_cvt_pk_bf16_f32 v201, v202, v203
	v_cvt_pk_bf16_f32 v204, v204, v205
	v_cvt_pk_bf16_f32 v205, v206, v207
	ds_write_b64 v11, v[200:201] offset:5120
	ds_write_b64 v11, v[204:205] offset:7680
	s_waitcnt lgkmcnt(0)
	s_barrier
	ds_read_b128 v[184:187], v10 offset:5120
	ds_read_b128 v[192:195], v10 offset:7680
	ds_read_b128 v[188:191], v10 offset:5184
	ds_read_b128 v[196:199], v10 offset:7744
	s_waitcnt vmcnt(0)
	v_lshlrev_b32_e32 v200, 16, v64
	v_and_b32_e32 v201, 0xffff0000, v64
	v_lshlrev_b32_e32 v202, 16, v65
	v_and_b32_e32 v203, 0xffff0000, v65
	v_lshlrev_b32_e32 v204, 16, v66
	v_and_b32_e32 v205, 0xffff0000, v66
	v_lshlrev_b32_e32 v206, 16, v67
	v_and_b32_e32 v207, 0xffff0000, v67
	s_waitcnt lgkmcnt(2)
	v_mfma_f32_16x16x32_bf16 v[200:203], v[56:59], v[184:187], v[200:203]
	v_mfma_f32_16x16x32_bf16 v[204:207], v[56:59], v[192:195], v[204:207]
	s_waitcnt lgkmcnt(0)
	v_mfma_f32_16x16x32_bf16 v[200:203], v[60:63], v[188:191], v[200:203]
	v_mfma_f32_16x16x32_bf16 v[204:207], v[60:63], v[196:199], v[204:207]
	s_nop 6
	v_cvt_pk_bf16_f32 v200, v200, v201
	v_cvt_pk_bf16_f32 v201, v202, v203
	v_cvt_pk_bf16_f32 v204, v204, v205
	v_cvt_pk_bf16_f32 v205, v206, v207
	ds_write_b64 v11, v[200:201]
	ds_write_b64 v11, v[204:205] offset:2560
	s_waitcnt lgkmcnt(0)
	s_barrier
